# attn prologue rope/gain loads pipelined 4 deep; p0 barrier uses xcd barrier instead of cg grid sync
# speedup vs baseline: 1.0047x; 1.0047x over previous
; __device__ __forceinline__ void attn_dense_body(const bf16* Qb, const bf16* __restrict__ Kh, const bf16* __restrict__ Vh,
;                                                 bf16* Ob, int seq, char* lds, const float* __restrict__ qg, const float* __restrict__ rope, int s0) {
;     ...
;   const bf16* Qw = Qb + (long)(wid * QBLK + r32) * LDQ + hi * 8;
; #pragma unroll
;   for (int d0 = 0; d0 < 8; ++d0) qr[d0] = ld8(Qw + d0 * 16);
;   {
;     float ss = 0.f;
; #pragma unroll
;     for (int d0 = 0; d0 < 8; ++d0)
; #pragma unroll
;       for (int e = 0; e < 8; ++e) { const float x = __uint_as_float((unsigned)(unsigned short)qr[d0][e] << 16); ss += x * x; }
;     { auto rr = __builtin_amdgcn_permlane32_swap(__float_as_uint(ss), __float_as_uint(ss), false, false); ss = __uint_as_float(rr[0]) + __uint_as_float(rr[1]); }
;     const float rstd = rsqrtf(ss * (1.f / 128.f) + 1e-6f) * (SCALE * 1.4426950408889634f);
;     const float* rp = rope + (long)(s0 + wid * QBLK + r32) * 128 + hi * 8;
;     const float* gp = qg + hi * 8;
; #pragma unroll
;     for (int d0 = 0; d0 < 8; ++d0) {
;       const float4 g0 = *reinterpret_cast<const float4*>(gp + d0 * 16), g1 = *reinterpret_cast<const float4*>(gp + d0 * 16 + 4);
;       const float4 c0 = *reinterpret_cast<const float4*>(rp + d0 * 16), c1 = *reinterpret_cast<const float4*>(rp + d0 * 16 + 4);
.LBB0_95:
	s_lshl_b32 s0, s19, 5
	s_ashr_i32 s28, s19, 2
	s_and_b32 s25, s19, 7
	s_and_b32 s26, s0, 0xf00
	s_and_b32 s0, s19, 0xffffff80
	s_and_b32 s28, s28, 0xffffff80
	s_ashr_i32 s1, s0, 31
	s_lshl_b32 s27, s25, 20
	s_ashr_i32 s29, s28, 31
	s_add_u32 s52, s27, s28
	s_addc_u32 s53, 0, s29
	s_lshl_b32 s25, s25, 23
	s_lshl_b32 s27, s26, 11
	s_or_b32 s25, s27, s25
	v_readlane_b32 s28, v255, 21
	v_readlane_b32 s29, v255, 22
	s_add_u32 s25, s28, s25
	s_addc_u32 s27, s29, 0
	s_lshl_b64 s[0:1], s[0:1], 1
	v_mov_b32_e32 v29, v196
	s_add_u32 s60, s25, s0
	s_movk_i32 s0, 0xffe0
	v_ashrrev_i32_e32 v2, 1, v29
	v_bfi_b32 v0, s0, v2, v29
	v_ashrrev_i32_e32 v1, 31, v0
	s_addc_u32 s61, s27, s1
	v_bfe_u32 v145, v29, 5, 1
	v_lshlrev_b64 v[0:1], 11, v[0:1]
	v_lshl_add_u64 v[0:1], s[60:61], 0, v[0:1]
	v_lshlrev_b32_e32 v194, 4, v145
	v_mov_b32_e32 v195, v144
	v_lshl_add_u64 v[0:1], v[0:1], 0, v[194:195]
	global_load_dwordx4 v[12:15], v[0:1], off offset:224
	global_load_dwordx4 v[18:21], v[0:1], off offset:192
	global_load_dwordx4 v[30:33], v[0:1], off offset:160
	global_load_dwordx4 v[36:39], v[0:1], off offset:128
	global_load_dwordx4 v[44:47], v[0:1], off offset:96
	global_load_dwordx4 v[52:55], v[0:1], off offset:64
	global_load_dwordx4 v[56:59], v[0:1], off offset:32
	global_load_dwordx4 v[60:63], v[0:1], off
	v_and_b32_e32 v195, 31, v29
	v_and_b32_e32 v192, 0xffffffe0, v2
	v_or_b32_e32 v0, s26, v195
	v_add_u32_e32 v0, v0, v192
	v_ashrrev_i32_e32 v1, 31, v0
	v_lshlrev_b64 v[0:1], 9, v[0:1]
	v_mov_b32_e32 v9, v144
	v_and_b32_e32 v8, 32, v29
	v_lshl_add_u64 v[0:1], s[54:55], 0, v[0:1]
	v_lshl_add_u64 v[10:11], v[0:1], 0, v[8:9]
	s_lshl_b64 s[0:1], s[52:53], 1
	s_add_u32 s56, s36, s0
	s_addc_u32 s27, s37, s1
	v_readlane_b32 s28, v255, 23
	v_readlane_b32 s29, v255, 24
	s_add_u32 s88, s28, s0
	s_addc_u32 s0, s29, s1
	s_add_i32 s25, 0, 0x10000
	s_cmp_lg_u32 0, -1
	s_cselect_b32 s26, 0, 0
	s_and_b32 s89, s0, 0xffff
	s_mov_b32 s95, s87
	s_mov_b32 s92, s88
	s_mov_b32 s93, s89
	s_mov_b32 s58, s94
	s_mov_b32 s59, s87
	s_and_b32 s57, s27, 0xffff
	v_lshlrev_b32_e32 v120, 4, v29
	v_lshlrev_b32_e32 v116, 8, v195
	v_and_b32_e32 v117, 0x70, v120
	v_or_b32_e32 v118, 0xe0, v194
	v_and_b32_e32 v121, 63, v29
	v_lshlrev_b32_e32 v123, 1, v29
	v_cmp_gt_u32_e64 s[52:53], 32, v121
	s_mov_b32 s66, s65
	s_mov_b32 s67, s65
	s_mov_b32 s68, s65
	s_mov_b32 s69, s65
	s_mov_b32 s70, s65
	s_mov_b32 s71, s65
	s_mov_b32 s72, s65
	s_mov_b32 s73, s65
	s_mov_b32 s74, s65
	s_mov_b32 s75, s65
	s_mov_b32 s76, s65
	s_mov_b32 s77, s65
	s_mov_b32 s79, s65
	v_and_b32_e32 v122, 0x3fffffc0, v29
	v_lshl_add_u32 v210, v122, 2, s25
	s_mov_b32 s0, -1
	v_mov_b32_e32 v193, 0
	v_mov_b32_e32 v228, 1.0
	s_mov_b32 s1, 0x18000
	v_lshl_add_u32 v211, v195, 2, v210
	s_waitcnt vmcnt(7)
	v_and_b32_e32 v1, 0xffff0000, v15
	v_lshlrev_b32_e32 v0, 16, v15
	v_and_b32_e32 v3, 0xffff0000, v14
	v_lshlrev_b32_e32 v2, 16, v14
	v_and_b32_e32 v5, 0xffff0000, v13
	v_lshlrev_b32_e32 v4, 16, v13
	v_and_b32_e32 v7, 0xffff0000, v12
	v_lshlrev_b32_e32 v6, 16, v12
	s_waitcnt vmcnt(6)
	v_and_b32_e32 v13, 0xffff0000, v21
	v_lshlrev_b32_e32 v12, 16, v21
	v_and_b32_e32 v15, 0xffff0000, v20
	v_lshlrev_b32_e32 v14, 16, v20
	s_waitcnt vmcnt(5)
	v_and_b32_e32 v21, 0xffff0000, v33
	v_lshlrev_b32_e32 v20, 16, v33
	v_and_b32_e32 v23, 0xffff0000, v32
	v_lshlrev_b32_e32 v22, 16, v32
	v_and_b32_e32 v25, 0xffff0000, v31
	v_lshlrev_b32_e32 v24, 16, v31
	v_and_b32_e32 v27, 0xffff0000, v30
	v_lshlrev_b32_e32 v26, 16, v30
	s_waitcnt vmcnt(4)
	v_and_b32_e32 v31, 0xffff0000, v39
	v_lshlrev_b32_e32 v30, 16, v39
	v_and_b32_e32 v33, 0xffff0000, v38
	v_lshlrev_b32_e32 v32, 16, v38
	s_waitcnt vmcnt(3)
	v_and_b32_e32 v39, 0xffff0000, v47
	v_lshlrev_b32_e32 v38, 16, v47
	v_and_b32_e32 v41, 0xffff0000, v46
	v_lshlrev_b32_e32 v40, 16, v46
	s_waitcnt vmcnt(2)
	v_and_b32_e32 v47, 0xffff0000, v55
	v_lshlrev_b32_e32 v46, 16, v55
	v_and_b32_e32 v49, 0xffff0000, v54
	v_lshlrev_b32_e32 v48, 16, v54
	s_waitcnt vmcnt(1)
	v_and_b32_e32 v81, 0xffff0000, v57
	v_lshlrev_b32_e32 v80, 16, v57
	v_and_b32_e32 v83, 0xffff0000, v56
	v_lshlrev_b32_e32 v82, 16, v56
	global_load_dwordx4 v[54:57], v8, s[16:17] offset:16
	global_load_dwordx4 v[64:67], v8, s[16:17]
	global_load_dwordx4 v[68:71], v[10:11], off offset:16
	global_load_dwordx4 v[72:75], v[10:11], off
	global_load_dwordx4 v[96:99], v8, s[16:17] offset:64
	global_load_dwordx4 v[100:103], v[10:11], off offset:64
	global_load_dwordx4 v[104:107], v8, s[16:17] offset:80
	global_load_dwordx4 v[108:111], v[10:11], off offset:80
	global_load_dwordx4 v[124:127], v8, s[16:17] offset:128
	global_load_dwordx4 v[128:131], v8, s[16:17] offset:144
	global_load_dwordx4 v[132:135], v[10:11], off offset:128
	global_load_dwordx4 v[136:139], v[10:11], off offset:144
	global_load_dwordx4 v[88:91], v8, s[16:17] offset:192
	global_load_dwordx4 v[92:95], v8, s[16:17] offset:208
	global_load_dwordx4 v[112:115], v[10:11], off offset:192
	global_load_dwordx4 v[140:143], v[10:11], off offset:208
	global_load_dwordx4 v[178:181], v8, s[16:17] offset:256
	global_load_dwordx4 v[182:185], v8, s[16:17] offset:272
	global_load_dwordx4 v[186:189], v[10:11], off offset:256
	global_load_dwordx4 v[242:245], v[10:11], off offset:272
	s_waitcnt vmcnt(20)
; __device__ __forceinline__ void attn_dense_body(const bf16* Qb, const bf16* __restrict__ Kh, const bf16* __restrict__ Vh,
;                                                 bf16* Ob, int seq, char* lds, const float* __restrict__ qg, const float* __restrict__ rope, int s0) {
;     ...
;     float ss = 0.f;
; #pragma unroll
;     for (int d0 = 0; d0 < 8; ++d0)
; #pragma unroll
;       for (int e = 0; e < 8; ++e) { const float x = __uint_as_float((unsigned)(unsigned short)qr[d0][e] << 16); ss += x * x; }
;     { auto rr = __builtin_amdgcn_permlane32_swap(__float_as_uint(ss), __float_as_uint(ss), false, false); ss = __uint_as_float(rr[0]) + __uint_as_float(rr[1]); }
;     const float rstd = rsqrtf(ss * (1.f / 128.f) + 1e-6f) * (SCALE * 1.4426950408889634f);
;     const float* rp = rope + (long)(s0 + wid * QBLK + r32) * 128 + hi * 8;
;     const float* gp = qg + hi * 8;
; #pragma unroll
;     for (int d0 = 0; d0 < 8; ++d0) {
;       const float4 g0 = *reinterpret_cast<const float4*>(gp + d0 * 16), g1 = *reinterpret_cast<const float4*>(gp + d0 * 16 + 4);
;       const float4 c0 = *reinterpret_cast<const float4*>(rp + d0 * 16), c1 = *reinterpret_cast<const float4*>(rp + d0 * 16 + 4);
;       const float gg[8] = {g0.x, g0.y, g0.z, g0.w, g1.x, g1.y, g1.z, g1.w};
;       const float cs[8] = {c0.x, c0.y, c0.z, c0.w, c1.x, c1.y, c1.z, c1.w};
;       unsigned w[4];
; #pragma unroll
;       for (int p = 0; p < 4; ++p) {
;         const float y0 = __uint_as_float((unsigned)(unsigned short)qr[d0][2 * p] << 16) * rstd * gg[2 * p], y1 = __uint_as_float((unsigned)(unsigned short)qr[d0][2 * p + 1] << 16) * rstd * gg[2 * p + 1];
	v_and_b32_e32 v85, 0xffff0000, v61
	v_lshlrev_b32_e32 v84, 16, v61
	v_and_b32_e32 v61, 0xffff0000, v60
	v_lshlrev_b32_e32 v60, 16, v60
	v_mul_f32_e32 v28, v61, v61
	v_pk_fma_f32 v[86:87], v[60:61], v[60:61], v[28:29] op_sel_hi:[1,1,0]
	v_mul_f32_e32 v28, v85, v85
	v_pk_fma_f32 v[86:87], v[84:85], v[84:85], v[86:87]
	v_and_b32_e32 v77, 0xffff0000, v59
	v_lshlrev_b32_e32 v76, 16, v59
	v_and_b32_e32 v79, 0xffff0000, v58
	v_lshlrev_b32_e32 v78, 16, v58
	v_and_b32_e32 v59, 0xffff0000, v63
	v_lshlrev_b32_e32 v58, 16, v63
	v_and_b32_e32 v63, 0xffff0000, v62
	v_lshlrev_b32_e32 v62, 16, v62
	v_pk_add_f32 v[86:87], v[28:29], v[86:87] op_sel_hi:[0,1]
	v_pk_fma_f32 v[86:87], v[62:63], v[62:63], v[86:87]
	v_mul_f32_e32 v28, v63, v63
	v_pk_add_f32 v[86:87], v[28:29], v[86:87] op_sel_hi:[0,1]
	v_pk_fma_f32 v[86:87], v[58:59], v[58:59], v[86:87]
	v_mul_f32_e32 v28, v59, v59
	v_pk_add_f32 v[86:87], v[28:29], v[86:87] op_sel_hi:[0,1]
	v_pk_fma_f32 v[86:87], v[82:83], v[82:83], v[86:87]
	v_mul_f32_e32 v28, v83, v83
	v_pk_add_f32 v[86:87], v[28:29], v[86:87] op_sel_hi:[0,1]
	v_pk_fma_f32 v[86:87], v[80:81], v[80:81], v[86:87]
	v_mul_f32_e32 v28, v81, v81
	v_pk_add_f32 v[86:87], v[28:29], v[86:87] op_sel_hi:[0,1]
	v_pk_fma_f32 v[86:87], v[78:79], v[78:79], v[86:87]
	v_mul_f32_e32 v28, v79, v79
	v_pk_add_f32 v[86:87], v[28:29], v[86:87] op_sel_hi:[0,1]
	v_pk_fma_f32 v[86:87], v[76:77], v[76:77], v[86:87]
	v_mul_f32_e32 v28, v77, v77
	v_and_b32_e32 v51, 0xffff0000, v53
	v_lshlrev_b32_e32 v50, 16, v53
	v_and_b32_e32 v53, 0xffff0000, v52
	v_lshlrev_b32_e32 v52, 16, v52
	v_pk_add_f32 v[86:87], v[28:29], v[86:87] op_sel_hi:[0,1]
	v_pk_fma_f32 v[86:87], v[52:53], v[52:53], v[86:87]
	v_mul_f32_e32 v28, v53, v53
	v_pk_add_f32 v[86:87], v[28:29], v[86:87] op_sel_hi:[0,1]
	v_pk_fma_f32 v[86:87], v[50:51], v[50:51], v[86:87]
	v_mul_f32_e32 v28, v51, v51
	v_pk_add_f32 v[86:87], v[28:29], v[86:87] op_sel_hi:[0,1]
	v_pk_fma_f32 v[86:87], v[48:49], v[48:49], v[86:87]
	v_mul_f32_e32 v28, v49, v49
	v_pk_add_f32 v[86:87], v[28:29], v[86:87] op_sel_hi:[0,1]
	v_pk_fma_f32 v[86:87], v[46:47], v[46:47], v[86:87]
	v_mul_f32_e32 v28, v47, v47
	v_and_b32_e32 v43, 0xffff0000, v45
	v_lshlrev_b32_e32 v42, 16, v45
	v_and_b32_e32 v45, 0xffff0000, v44
	v_lshlrev_b32_e32 v44, 16, v44
	v_pk_add_f32 v[86:87], v[28:29], v[86:87] op_sel_hi:[0,1]
	v_pk_fma_f32 v[86:87], v[44:45], v[44:45], v[86:87]
	v_mul_f32_e32 v28, v45, v45
	v_pk_add_f32 v[86:87], v[28:29], v[86:87] op_sel_hi:[0,1]
	v_pk_fma_f32 v[86:87], v[42:43], v[42:43], v[86:87]
	v_mul_f32_e32 v28, v43, v43
	v_pk_add_f32 v[86:87], v[28:29], v[86:87] op_sel_hi:[0,1]
	v_pk_fma_f32 v[86:87], v[40:41], v[40:41], v[86:87]
	v_mul_f32_e32 v28, v41, v41
	v_pk_add_f32 v[86:87], v[28:29], v[86:87] op_sel_hi:[0,1]
	v_pk_fma_f32 v[86:87], v[38:39], v[38:39], v[86:87]
	v_mul_f32_e32 v28, v39, v39
	v_and_b32_e32 v35, 0xffff0000, v37
	v_lshlrev_b32_e32 v34, 16, v37
	v_and_b32_e32 v37, 0xffff0000, v36
	v_lshlrev_b32_e32 v36, 16, v36
	v_pk_add_f32 v[86:87], v[28:29], v[86:87] op_sel_hi:[0,1]
	v_pk_fma_f32 v[86:87], v[36:37], v[36:37], v[86:87]
	v_mul_f32_e32 v28, v37, v37
	v_pk_add_f32 v[86:87], v[28:29], v[86:87] op_sel_hi:[0,1]
	v_pk_fma_f32 v[86:87], v[34:35], v[34:35], v[86:87]
	v_mul_f32_e32 v28, v35, v35
	v_pk_add_f32 v[86:87], v[28:29], v[86:87] op_sel_hi:[0,1]
	v_pk_fma_f32 v[86:87], v[32:33], v[32:33], v[86:87]
	v_mul_f32_e32 v28, v33, v33
	v_pk_add_f32 v[86:87], v[28:29], v[86:87] op_sel_hi:[0,1]
	v_pk_fma_f32 v[86:87], v[30:31], v[30:31], v[86:87]
	v_mul_f32_e32 v28, v31, v31
	v_pk_add_f32 v[86:87], v[28:29], v[86:87] op_sel_hi:[0,1]
	v_pk_fma_f32 v[86:87], v[26:27], v[26:27], v[86:87]
	v_mul_f32_e32 v28, v27, v27
	v_pk_add_f32 v[86:87], v[28:29], v[86:87] op_sel_hi:[0,1]
	v_pk_fma_f32 v[86:87], v[24:25], v[24:25], v[86:87]
	v_mul_f32_e32 v28, v25, v25
	v_pk_add_f32 v[86:87], v[28:29], v[86:87] op_sel_hi:[0,1]
	v_pk_fma_f32 v[86:87], v[22:23], v[22:23], v[86:87]
	v_mul_f32_e32 v28, v23, v23
	v_pk_add_f32 v[86:87], v[28:29], v[86:87] op_sel_hi:[0,1]
	v_pk_fma_f32 v[86:87], v[20:21], v[20:21], v[86:87]
	v_mul_f32_e32 v28, v21, v21
	v_and_b32_e32 v17, 0xffff0000, v19
	v_lshlrev_b32_e32 v16, 16, v19
	v_and_b32_e32 v19, 0xffff0000, v18
	v_lshlrev_b32_e32 v18, 16, v18
	v_pk_add_f32 v[86:87], v[28:29], v[86:87] op_sel_hi:[0,1]
	v_pk_fma_f32 v[86:87], v[18:19], v[18:19], v[86:87]
	v_mul_f32_e32 v28, v19, v19
	v_pk_add_f32 v[86:87], v[28:29], v[86:87] op_sel_hi:[0,1]
	v_pk_fma_f32 v[86:87], v[16:17], v[16:17], v[86:87]
	v_mul_f32_e32 v28, v17, v17
	v_pk_add_f32 v[86:87], v[28:29], v[86:87] op_sel_hi:[0,1]
	v_pk_fma_f32 v[86:87], v[14:15], v[14:15], v[86:87]
	v_mul_f32_e32 v28, v15, v15
	v_pk_add_f32 v[86:87], v[28:29], v[86:87] op_sel_hi:[0,1]
	v_pk_fma_f32 v[86:87], v[12:13], v[12:13], v[86:87]
	v_mul_f32_e32 v28, v13, v13
	v_pk_add_f32 v[86:87], v[28:29], v[86:87] op_sel_hi:[0,1]
	v_pk_fma_f32 v[86:87], v[6:7], v[6:7], v[86:87]
	v_mul_f32_e32 v28, v7, v7
	v_pk_add_f32 v[86:87], v[28:29], v[86:87] op_sel_hi:[0,1]
	v_pk_fma_f32 v[86:87], v[4:5], v[4:5], v[86:87]
	v_mul_f32_e32 v28, v5, v5
	v_pk_add_f32 v[86:87], v[28:29], v[86:87] op_sel_hi:[0,1]
	v_pk_fma_f32 v[86:87], v[2:3], v[2:3], v[86:87]
	v_mul_f32_e32 v28, v3, v3
	v_pk_add_f32 v[86:87], v[28:29], v[86:87] op_sel_hi:[0,1]
	v_pk_fma_f32 v[86:87], v[0:1], v[0:1], v[86:87]
	v_mul_f32_e32 v28, v1, v1
	v_pk_add_f32 v[86:87], v[28:29], v[86:87] op_sel_hi:[0,1]
	v_mov_b32_e32 v9, v86
	s_nop 1
	v_permlane32_swap_b32_e32 v86, v9
	v_add_f32_e32 v9, v86, v9
	v_fmamk_f32 v9, v9, 0x3c000000, v197
	v_mul_f32_e32 v28, 0x4b800000, v9
	v_cmp_gt_f32_e32 vcc, s78, v9
	s_mov_b32 s78, s65
	s_nop 0
	v_cndmask_b32_e32 v9, v9, v28, vcc
	v_rsq_f32_e32 v9, v9
	s_nop 0
	v_mul_f32_e32 v28, 0x45800000, v9
	v_cndmask_b32_e32 v9, v9, v28, vcc
	v_mul_f32_e32 v28, 0x3e0293ee, v9
	v_pk_mul_f32 v[60:61], v[28:29], v[60:61] op_sel_hi:[0,1]
	s_waitcnt vmcnt(18)
; __device__ __forceinline__ void attn_dense_body(const bf16* Qb, const bf16* __restrict__ Kh, const bf16* __restrict__ Vh,
;                                                 bf16* Ob, int seq, char* lds, const float* __restrict__ qg, const float* __restrict__ rope, int s0) {
;     ...
;     for (int d0 = 0; d0 < 8; ++d0) {
;       const float4 g0 = *reinterpret_cast<const float4*>(gp + d0 * 16), g1 = *reinterpret_cast<const float4*>(gp + d0 * 16 + 4);
;       const float4 c0 = *reinterpret_cast<const float4*>(rp + d0 * 16), c1 = *reinterpret_cast<const float4*>(rp + d0 * 16 + 4);
;       const float gg[8] = {g0.x, g0.y, g0.z, g0.w, g1.x, g1.y, g1.z, g1.w};
;       const float cs[8] = {c0.x, c0.y, c0.z, c0.w, c1.x, c1.y, c1.z, c1.w};
;       unsigned w[4];
; #pragma unroll
;       for (int p = 0; p < 4; ++p) {
;         const float y0 = __uint_as_float((unsigned)(unsigned short)qr[d0][2 * p] << 16) * rstd * gg[2 * p], y1 = __uint_as_float((unsigned)(unsigned short)qr[d0][2 * p + 1] << 16) * rstd * gg[2 * p + 1];
;         w[p] = cvtpk(y0 * cs[2 * p] - y1 * cs[2 * p + 1], y0 * cs[2 * p + 1] + y1 * cs[2 * p]);
;       }
;       u32x4 ww = {w[0], w[1], w[2], w[3]}; qr[d0] = *reinterpret_cast<bf16x8*>(&ww);
	v_pk_mul_f32 v[60:61], v[64:65], v[60:61]
	v_pk_mul_f32 v[52:53], v[28:29], v[52:53] op_sel_hi:[0,1]
	s_waitcnt vmcnt(16)
	v_pk_mul_f32 v[64:65], v[72:73], v[60:61]
	v_pk_mul_f32 v[60:61], v[72:73], v[60:61] op_sel:[0,1] op_sel_hi:[1,0]
	v_sub_f32_e32 v9, v64, v65
	v_add_f32_e32 v60, v60, v61
	v_cvt_pk_bf16_f32 v146, v9, v60
	v_pk_mul_f32 v[60:61], v[28:29], v[84:85] op_sel_hi:[0,1]
	v_pk_mul_f32 v[60:61], v[66:67], v[60:61]
	v_pk_mul_f32 v[50:51], v[28:29], v[50:51] op_sel_hi:[0,1]
	v_pk_mul_f32 v[64:65], v[74:75], v[60:61]
	v_pk_mul_f32 v[60:61], v[74:75], v[60:61] op_sel:[0,1] op_sel_hi:[1,0]
	v_sub_f32_e32 v9, v64, v65
	v_add_f32_e32 v60, v60, v61
	v_cvt_pk_bf16_f32 v147, v9, v60
	v_pk_mul_f32 v[60:61], v[28:29], v[62:63] op_sel_hi:[0,1]
	v_pk_mul_f32 v[54:55], v[54:55], v[60:61]
	v_pk_mul_f32 v[48:49], v[28:29], v[48:49] op_sel_hi:[0,1]
	v_pk_mul_f32 v[60:61], v[54:55], v[68:69]
	v_pk_mul_f32 v[54:55], v[54:55], v[68:69] op_sel:[1,0] op_sel_hi:[0,1]
	v_add_f32_e32 v54, v54, v55
	v_sub_f32_e32 v9, v60, v61
	v_cvt_pk_bf16_f32 v148, v9, v54
	v_pk_mul_f32 v[54:55], v[28:29], v[58:59] op_sel_hi:[0,1]
	v_pk_mul_f32 v[54:55], v[56:57], v[54:55]
	v_pk_mul_f32 v[46:47], v[28:29], v[46:47] op_sel_hi:[0,1]
	v_pk_mul_f32 v[56:57], v[54:55], v[70:71]
	v_pk_mul_f32 v[54:55], v[54:55], v[70:71] op_sel:[1,0] op_sel_hi:[0,1]
	v_add_f32_e32 v54, v54, v55
	v_sub_f32_e32 v9, v56, v57
	v_cvt_pk_bf16_f32 v149, v9, v54
	v_pk_mul_f32 v[70:71], v[28:29], v[82:83] op_sel_hi:[0,1]
	v_pk_mul_f32 v[44:45], v[28:29], v[44:45] op_sel_hi:[0,1]
	v_pk_mul_f32 v[42:43], v[28:29], v[42:43] op_sel_hi:[0,1]
	v_pk_mul_f32 v[40:41], v[28:29], v[40:41] op_sel_hi:[0,1]
	v_pk_mul_f32 v[38:39], v[28:29], v[38:39] op_sel_hi:[0,1]
	v_pk_mul_f32 v[36:37], v[28:29], v[36:37] op_sel_hi:[0,1]
	v_pk_mul_f32 v[34:35], v[28:29], v[34:35] op_sel_hi:[0,1]
	v_pk_mul_f32 v[32:33], v[28:29], v[32:33] op_sel_hi:[0,1]
	v_pk_mul_f32 v[30:31], v[28:29], v[30:31] op_sel_hi:[0,1]
	v_pk_mul_f32 v[26:27], v[28:29], v[26:27] op_sel_hi:[0,1]
	v_pk_mul_f32 v[24:25], v[28:29], v[24:25] op_sel_hi:[0,1]
	v_pk_mul_f32 v[22:23], v[28:29], v[22:23] op_sel_hi:[0,1]
	v_pk_mul_f32 v[20:21], v[28:29], v[20:21] op_sel_hi:[0,1]
	v_pk_mul_f32 v[18:19], v[28:29], v[18:19] op_sel_hi:[0,1]
	v_pk_mul_f32 v[16:17], v[28:29], v[16:17] op_sel_hi:[0,1]
	v_pk_mul_f32 v[14:15], v[28:29], v[14:15] op_sel_hi:[0,1]
	v_pk_mul_f32 v[12:13], v[28:29], v[12:13] op_sel_hi:[0,1]
	v_pk_mul_f32 v[6:7], v[28:29], v[6:7] op_sel_hi:[0,1]
	v_pk_mul_f32 v[4:5], v[28:29], v[4:5] op_sel_hi:[0,1]
	v_pk_mul_f32 v[2:3], v[28:29], v[2:3] op_sel_hi:[0,1]
	v_pk_mul_f32 v[0:1], v[28:29], v[0:1] op_sel_hi:[0,1]
	s_waitcnt vmcnt(15)
	v_pk_mul_f32 v[54:55], v[70:71], v[96:97]
	s_waitcnt vmcnt(14)
	v_pk_mul_f32 v[70:71], v[54:55], v[100:101]
	v_pk_mul_f32 v[54:55], v[54:55], v[100:101] op_sel:[1,0] op_sel_hi:[0,1]
	v_add_f32_e32 v54, v54, v55
	v_sub_f32_e32 v9, v70, v71
	v_cvt_pk_bf16_f32 v150, v9, v54
	v_pk_mul_f32 v[54:55], v[28:29], v[80:81] op_sel_hi:[0,1]
	v_pk_mul_f32 v[54:55], v[54:55], v[98:99]
	s_nop 0
	v_pk_mul_f32 v[56:57], v[54:55], v[102:103]
	v_pk_mul_f32 v[54:55], v[54:55], v[102:103] op_sel:[1,0] op_sel_hi:[0,1]
	v_add_f32_e32 v54, v54, v55
	v_sub_f32_e32 v9, v56, v57
	v_cvt_pk_bf16_f32 v151, v9, v54
	v_pk_mul_f32 v[54:55], v[28:29], v[78:79] op_sel_hi:[0,1]
	s_waitcnt vmcnt(13)
	v_pk_mul_f32 v[54:55], v[54:55], v[104:105]
	s_waitcnt vmcnt(12)
	v_pk_mul_f32 v[56:57], v[54:55], v[108:109]
	v_pk_mul_f32 v[54:55], v[54:55], v[108:109] op_sel:[1,0] op_sel_hi:[0,1]
	v_add_f32_e32 v54, v54, v55
	v_sub_f32_e32 v9, v56, v57
	v_cvt_pk_bf16_f32 v152, v9, v54
	v_pk_mul_f32 v[54:55], v[28:29], v[76:77] op_sel_hi:[0,1]
	v_pk_mul_f32 v[54:55], v[54:55], v[106:107]
	s_nop 0
	v_pk_mul_f32 v[56:57], v[54:55], v[110:111]
	v_pk_mul_f32 v[54:55], v[54:55], v[110:111] op_sel:[1,0] op_sel_hi:[0,1]
	v_add_f32_e32 v54, v54, v55
	v_sub_f32_e32 v9, v56, v57
	v_cvt_pk_bf16_f32 v153, v9, v54
	global_load_dwordx4 v[96:99], v8, s[16:17] offset:320
	global_load_dwordx4 v[100:103], v8, s[16:17] offset:336
	global_load_dwordx4 v[104:107], v[10:11], off offset:320
	global_load_dwordx4 v[108:111], v[10:11], off offset:336
	s_waitcnt vmcnt(15)
	v_pk_mul_f32 v[52:53], v[52:53], v[124:125]
	v_pk_mul_f32 v[50:51], v[50:51], v[126:127]
	s_waitcnt vmcnt(14)
	v_pk_mul_f32 v[48:49], v[48:49], v[128:129]
	v_pk_mul_f32 v[46:47], v[46:47], v[130:131]
	s_waitcnt vmcnt(13)
	v_pk_mul_f32 v[54:55], v[52:53], v[132:133]
	v_pk_mul_f32 v[52:53], v[52:53], v[132:133] op_sel:[1,0] op_sel_hi:[0,1]
	v_pk_mul_f32 v[56:57], v[50:51], v[134:135]
	v_pk_mul_f32 v[50:51], v[50:51], v[134:135] op_sel:[1,0] op_sel_hi:[0,1]
	s_waitcnt vmcnt(12)
	v_pk_mul_f32 v[58:59], v[48:49], v[136:137]
	v_pk_mul_f32 v[48:49], v[48:49], v[136:137] op_sel:[1,0] op_sel_hi:[0,1]
	v_pk_mul_f32 v[60:61], v[46:47], v[138:139]
	v_pk_mul_f32 v[46:47], v[46:47], v[138:139] op_sel:[1,0] op_sel_hi:[0,1]
	v_add_f32_e32 v52, v52, v53
	v_sub_f32_e32 v53, v56, v57
	v_add_f32_e32 v50, v50, v51
	v_sub_f32_e32 v51, v58, v59
	v_add_f32_e32 v48, v48, v49
	v_sub_f32_e32 v49, v60, v61
	v_add_f32_e32 v46, v46, v47
	v_sub_f32_e32 v9, v54, v55
	v_cvt_pk_bf16_f32 v154, v9, v52
	v_cvt_pk_bf16_f32 v155, v53, v50
	v_cvt_pk_bf16_f32 v156, v51, v48
	v_cvt_pk_bf16_f32 v157, v49, v46
	global_load_dwordx4 v[124:127], v8, s[16:17] offset:384
	global_load_dwordx4 v[128:131], v8, s[16:17] offset:400
	global_load_dwordx4 v[132:135], v[10:11], off offset:384
	global_load_dwordx4 v[136:139], v[10:11], off offset:400
	s_waitcnt vmcnt(15)
	v_pk_mul_f32 v[44:45], v[44:45], v[88:89]
	v_pk_mul_f32 v[42:43], v[42:43], v[90:91]
	s_waitcnt vmcnt(14)
; __device__ __forceinline__ void attn_dense_body(const bf16* Qb, const bf16* __restrict__ Kh, const bf16* __restrict__ Vh,
;                                                 bf16* Ob, int seq, char* lds, const float* __restrict__ qg, const float* __restrict__ rope, int s0) {
;     ...
;     for (int d0 = 0; d0 < 8; ++d0) {
;       const float4 g0 = *reinterpret_cast<const float4*>(gp + d0 * 16), g1 = *reinterpret_cast<const float4*>(gp + d0 * 16 + 4);
;       const float4 c0 = *reinterpret_cast<const float4*>(rp + d0 * 16), c1 = *reinterpret_cast<const float4*>(rp + d0 * 16 + 4);
;       const float gg[8] = {g0.x, g0.y, g0.z, g0.w, g1.x, g1.y, g1.z, g1.w};
;       const float cs[8] = {c0.x, c0.y, c0.z, c0.w, c1.x, c1.y, c1.z, c1.w};
;       unsigned w[4];
; #pragma unroll
;       for (int p = 0; p < 4; ++p) {
;         const float y0 = __uint_as_float((unsigned)(unsigned short)qr[d0][2 * p] << 16) * rstd * gg[2 * p], y1 = __uint_as_float((unsigned)(unsigned short)qr[d0][2 * p + 1] << 16) * rstd * gg[2 * p + 1];
;         w[p] = cvtpk(y0 * cs[2 * p] - y1 * cs[2 * p + 1], y0 * cs[2 * p + 1] + y1 * cs[2 * p]);
;       }
;       u32x4 ww = {w[0], w[1], w[2], w[3]}; qr[d0] = *reinterpret_cast<bf16x8*>(&ww);
	v_pk_mul_f32 v[40:41], v[40:41], v[92:93]
	v_pk_mul_f32 v[38:39], v[38:39], v[94:95]
	s_waitcnt vmcnt(13)
	v_pk_mul_f32 v[46:47], v[44:45], v[112:113]
	v_pk_mul_f32 v[44:45], v[44:45], v[112:113] op_sel:[1,0] op_sel_hi:[0,1]
	v_pk_mul_f32 v[48:49], v[42:43], v[114:115]
	v_pk_mul_f32 v[42:43], v[42:43], v[114:115] op_sel:[1,0] op_sel_hi:[0,1]
	s_waitcnt vmcnt(12)
	v_pk_mul_f32 v[50:51], v[40:41], v[140:141]
	v_pk_mul_f32 v[40:41], v[40:41], v[140:141] op_sel:[1,0] op_sel_hi:[0,1]
	v_pk_mul_f32 v[52:53], v[38:39], v[142:143]
	v_pk_mul_f32 v[38:39], v[38:39], v[142:143] op_sel:[1,0] op_sel_hi:[0,1]
	v_add_f32_e32 v44, v44, v45
	v_sub_f32_e32 v45, v48, v49
	v_add_f32_e32 v42, v42, v43
	v_sub_f32_e32 v43, v50, v51
	v_add_f32_e32 v40, v40, v41
	v_sub_f32_e32 v41, v52, v53
	v_add_f32_e32 v38, v38, v39
	v_sub_f32_e32 v9, v46, v47
	v_cvt_pk_bf16_f32 v158, v9, v44
	v_cvt_pk_bf16_f32 v159, v45, v42
	v_cvt_pk_bf16_f32 v160, v43, v40
	v_cvt_pk_bf16_f32 v161, v41, v38
	global_load_dwordx4 v[88:91], v8, s[16:17] offset:448
	global_load_dwordx4 v[92:95], v8, s[16:17] offset:464
	global_load_dwordx4 v[112:115], v[10:11], off offset:448
	global_load_dwordx4 v[140:143], v[10:11], off offset:464
	s_waitcnt vmcnt(15)
	v_pk_mul_f32 v[36:37], v[36:37], v[178:179]
	v_pk_mul_f32 v[34:35], v[34:35], v[180:181]
	s_waitcnt vmcnt(14)
	v_pk_mul_f32 v[32:33], v[32:33], v[182:183]
	v_pk_mul_f32 v[30:31], v[30:31], v[184:185]
	s_waitcnt vmcnt(13)
	v_pk_mul_f32 v[38:39], v[36:37], v[186:187]
	v_pk_mul_f32 v[36:37], v[36:37], v[186:187] op_sel:[1,0] op_sel_hi:[0,1]
	v_pk_mul_f32 v[40:41], v[34:35], v[188:189]
	v_pk_mul_f32 v[34:35], v[34:35], v[188:189] op_sel:[1,0] op_sel_hi:[0,1]
	s_waitcnt vmcnt(12)
	v_pk_mul_f32 v[42:43], v[32:33], v[242:243]
	v_pk_mul_f32 v[32:33], v[32:33], v[242:243] op_sel:[1,0] op_sel_hi:[0,1]
	v_pk_mul_f32 v[44:45], v[30:31], v[244:245]
	v_pk_mul_f32 v[30:31], v[30:31], v[244:245] op_sel:[1,0] op_sel_hi:[0,1]
	v_add_f32_e32 v36, v36, v37
	v_sub_f32_e32 v37, v40, v41
	v_add_f32_e32 v34, v34, v35
	v_sub_f32_e32 v35, v42, v43
	v_add_f32_e32 v32, v32, v33
	v_sub_f32_e32 v33, v44, v45
	v_add_f32_e32 v30, v30, v31
	v_sub_f32_e32 v9, v38, v39
	v_cvt_pk_bf16_f32 v162, v9, v36
	v_cvt_pk_bf16_f32 v163, v37, v34
	v_cvt_pk_bf16_f32 v164, v35, v32
	v_cvt_pk_bf16_f32 v165, v33, v30
	s_waitcnt vmcnt(11)
	v_pk_mul_f32 v[26:27], v[26:27], v[96:97]
	v_pk_mul_f32 v[24:25], v[24:25], v[98:99]
	s_waitcnt vmcnt(10)
	v_pk_mul_f32 v[22:23], v[22:23], v[100:101]
	v_pk_mul_f32 v[20:21], v[20:21], v[102:103]
	s_waitcnt vmcnt(9)
	v_pk_mul_f32 v[30:31], v[26:27], v[104:105]
	v_pk_mul_f32 v[26:27], v[26:27], v[104:105] op_sel:[1,0] op_sel_hi:[0,1]
	v_pk_mul_f32 v[32:33], v[24:25], v[106:107]
	v_pk_mul_f32 v[24:25], v[24:25], v[106:107] op_sel:[1,0] op_sel_hi:[0,1]
	s_waitcnt vmcnt(8)
	v_pk_mul_f32 v[34:35], v[22:23], v[108:109]
	v_pk_mul_f32 v[22:23], v[22:23], v[108:109] op_sel:[1,0] op_sel_hi:[0,1]
	v_pk_mul_f32 v[36:37], v[20:21], v[110:111]
	v_pk_mul_f32 v[20:21], v[20:21], v[110:111] op_sel:[1,0] op_sel_hi:[0,1]
	v_add_f32_e32 v26, v26, v27
	v_sub_f32_e32 v27, v32, v33
	v_add_f32_e32 v24, v24, v25
	v_sub_f32_e32 v25, v34, v35
	v_add_f32_e32 v22, v22, v23
	v_sub_f32_e32 v23, v36, v37
	v_add_f32_e32 v20, v20, v21
	v_sub_f32_e32 v9, v30, v31
	v_cvt_pk_bf16_f32 v166, v9, v26
	v_cvt_pk_bf16_f32 v167, v27, v24
	v_cvt_pk_bf16_f32 v168, v25, v22
	v_cvt_pk_bf16_f32 v169, v23, v20
	s_waitcnt vmcnt(7)
	v_pk_mul_f32 v[18:19], v[18:19], v[124:125]
	v_pk_mul_f32 v[16:17], v[16:17], v[126:127]
	s_waitcnt vmcnt(6)
	v_pk_mul_f32 v[14:15], v[14:15], v[128:129]
	v_pk_mul_f32 v[12:13], v[12:13], v[130:131]
	s_waitcnt vmcnt(5)
	v_pk_mul_f32 v[20:21], v[18:19], v[132:133]
	v_pk_mul_f32 v[18:19], v[18:19], v[132:133] op_sel:[1,0] op_sel_hi:[0,1]
	v_pk_mul_f32 v[22:23], v[16:17], v[134:135]
	v_pk_mul_f32 v[16:17], v[16:17], v[134:135] op_sel:[1,0] op_sel_hi:[0,1]
	s_waitcnt vmcnt(4)
	v_pk_mul_f32 v[24:25], v[14:15], v[136:137]
	v_pk_mul_f32 v[14:15], v[14:15], v[136:137] op_sel:[1,0] op_sel_hi:[0,1]
	v_pk_mul_f32 v[26:27], v[12:13], v[138:139]
	v_pk_mul_f32 v[12:13], v[12:13], v[138:139] op_sel:[1,0] op_sel_hi:[0,1]
	v_sub_f32_e32 v9, v20, v21
	v_add_f32_e32 v18, v18, v19
	v_sub_f32_e32 v19, v22, v23
	v_add_f32_e32 v16, v16, v17
	v_sub_f32_e32 v17, v24, v25
	v_add_f32_e32 v14, v14, v15
	v_sub_f32_e32 v15, v26, v27
	v_add_f32_e32 v12, v12, v13
	v_cvt_pk_bf16_f32 v170, v9, v18
	v_cvt_pk_bf16_f32 v171, v19, v16
	v_cvt_pk_bf16_f32 v172, v17, v14
	v_cvt_pk_bf16_f32 v173, v15, v12
	s_nop 0
	v_ashrrev_i32_e32 v24, 4, v29
	v_lshlrev_b32_e32 v25, 3, v29
	v_and_b32_e32 v26, 0x78, v25
	v_lshlrev_b32_e32 v27, 8, v24
	v_or_b32_e32 v30, v27, v26
	v_lshlrev_b32_e32 v214, 1, v30
	v_add_u32_e32 v215, 0x4000, v214
	s_waitcnt vmcnt(3)
	v_pk_mul_f32 v[6:7], v[6:7], v[88:89]
	v_pk_mul_f32 v[4:5], v[4:5], v[90:91]
	s_waitcnt vmcnt(2)
	v_pk_mul_f32 v[2:3], v[2:3], v[92:93]
	v_pk_mul_f32 v[0:1], v[0:1], v[94:95]
	s_waitcnt vmcnt(1)
	v_pk_mul_f32 v[12:13], v[6:7], v[112:113]
	v_pk_mul_f32 v[6:7], v[6:7], v[112:113] op_sel:[1,0] op_sel_hi:[0,1]
	v_pk_mul_f32 v[14:15], v[4:5], v[114:115]
	v_pk_mul_f32 v[4:5], v[4:5], v[114:115] op_sel:[1,0] op_sel_hi:[0,1]
	s_waitcnt vmcnt(0)
; __device__ __forceinline__ int v_st(int k, int c) { const int kk = (k & ~0xC) | ((k & 4) << 1) | ((k & 8) >> 1); return ((kk >> 3) * 4 + (c >> 5)) * 512 + ((kk & 7) * 32 + (c & 31)) * 2; }
; __device__ __forceinline__ int v_rd_base(int lane) { return ((lane & 3) << 3) | (((lane >> 2) & 3) << 6) | (((lane >> 4) & 1) << 5) | (((lane >> 5) & 1) << 8); }
; __device__ __forceinline__ void qkt(f32x16& p0, f32x16& p1, const bf16* Ks, const bf16x8* qr, const f32x16& negm, int r32, int hi) {
; #pragma unroll
;   for (int d0 = 0; d0 < 8; ++d0) { int cb = (d0 * 16 + hi * 8) * 2;
;     bf16x8 b0 = *reinterpret_cast<const bf16x8*>((const char*)Ks + KSWZ(r32, cb));
;     bf16x8 b1 = *reinterpret_cast<const bf16x8*>((const char*)Ks + KSWZ(32 + r32, cb));
;     if (d0 == 0) { p0 = __builtin_amdgcn_mfma_f32_32x32x16_bf16(b0, qr[0], negm, 0, 0, 0); p1 = __builtin_amdgcn_mfma_f32_32x32x16_bf16(b1, qr[0], negm, 0, 0, 0); }
;     else { p0 = __builtin_amdgcn_mfma_f32_32x32x16_bf16(b0, qr[d0], p0, 0, 0, 0); p1 = __builtin_amdgcn_mfma_f32_32x32x16_bf16(b1, qr[d0], p1, 0, 0, 0); } }
; }
; __device__ __forceinline__ void attn_dense_body(const bf16* Qb, const bf16* __restrict__ Kh, const bf16* __restrict__ Vh,
;                                                 bf16* Ob, int seq, char* lds, const float* __restrict__ qg, const float* __restrict__ rope, int s0) {
;     ...
;   const int sr = tid >> 4, sc = (tid & 15) * 8, vst0 = v_st(sr, sc), vst1 = v_st(32 + sr, sc);
;   const int vb0 = (int)(uintptr_t)V_lds + v_rd_base(lane);
;   struct { bf16x8 vs0, vs1, ks0, ks1; } sr_[1];
;   const __amdgpu_buffer_rsrc_t srK = __builtin_amdgcn_make_buffer_rsrc((void*)Kh, (short)0, seq * LDK * 2, 0x00020000);
;   const __amdgpu_buffer_rsrc_t srV = __builtin_amdgcn_make_buffer_rsrc((void*)Vh, (short)0, seq * LDK * 2, 0x00020000);
;   const unsigned kvoff = (unsigned)(sr * LDK + sc) * 2u;
;     ...
;   f32x16 pA0, pA1, pB0, pB1; float alA, alB; bf16x8 pa0, pa1, pa2, pa3; const int NT = seq / KVBLK;
;   constexpr int SE = 0, SO = 0;
;   SLOAD(SE, 0); asm volatile("s_waitcnt vmcnt(0)" ::: "memory"); SWRITE(0, SE); __syncthreads();
;   qkt(pA0, pA1, K_lds, qr, negm, r32, hi); partialSM<true>(pA0, pA1, m_reg, negm, alA);
;   SLOAD(SO, KVBLK);
	v_pk_mul_f32 v[16:17], v[2:3], v[140:141]
	v_pk_mul_f32 v[2:3], v[2:3], v[140:141] op_sel:[1,0] op_sel_hi:[0,1]
	v_pk_mul_f32 v[8:9], v[0:1], v[142:143]
	v_pk_mul_f32 v[0:1], v[0:1], v[142:143] op_sel:[1,0] op_sel_hi:[0,1]
	v_sub_f32_e32 v10, v12, v13
	v_add_f32_e32 v6, v6, v7
	v_sub_f32_e32 v7, v14, v15
	v_add_f32_e32 v4, v4, v5
	v_sub_f32_e32 v5, v16, v17
	v_add_f32_e32 v2, v2, v3
	v_sub_f32_e32 v3, v8, v9
	v_add_f32_e32 v0, v0, v1
	v_cvt_pk_bf16_f32 v174, v10, v6
	v_cvt_pk_bf16_f32 v175, v7, v4
	v_cvt_pk_bf16_f32 v176, v5, v2
	v_cvt_pk_bf16_f32 v177, v3, v0
	buffer_load_dwordx4 v[0:3], v214, s[92:95], 0 offen
	buffer_load_dwordx4 v[4:7], v215, s[92:95], 0 offen
	buffer_load_dwordx4 v[8:11], v214, s[56:59], 0 offen
	buffer_load_dwordx4 v[12:15], v215, s[56:59], 0 offen
	v_and_b32_e32 v17, 0xfffff0, v24
	v_lshlrev_b32_e32 v18, 1, v24
	v_lshrrev_b32_e32 v19, 1, v24
	v_and_b32_e32 v21, 3, v24
	v_add_u32_e32 v22, 32, v24
	v_and_or_b32 v17, v18, 8, v17
	v_and_or_b32 v18, v19, 4, v21
	v_and_b32_e32 v21, 0xfffff0, v22
	v_lshlrev_b32_e32 v23, 1, v22
	v_and_b32_e32 v16, 0x70, v29
	v_bfe_u32 v20, v25, 5, 2
	v_lshlrev_b32_e32 v19, 1, v26
	v_lshlrev_b32_e32 v22, 8, v22
	v_lshrrev_b32_e32 v17, 1, v17
	v_and_or_b32 v21, v23, 8, v21
	v_and_b32_e32 v25, 48, v19
	v_bitop3_b32 v23, v19, v27, v16 bitop3:0xde
	v_bitop3_b32 v16, v19, v22, v16 bitop3:0xde
	v_or_b32_e32 v17, v17, v20
	v_lshrrev_b32_e32 v19, 1, v21
	v_lshlrev_b32_e32 v18, 6, v18
	v_add_u32_e32 v218, 0, v16
	v_lshlrev_b32_e32 v16, 9, v17
	v_or_b32_e32 v17, v19, v20
	v_bitop3_b32 v24, v194, v116, v117 bitop3:0xde
	v_or3_b32 v16, v16, v18, v25
	v_lshlrev_b32_e32 v17, 9, v17
	v_add_u32_e32 v216, 0, v24
	v_or3_b32 v17, v17, v18, v25
	v_add_u32_e32 v219, 0, v16
	v_add_u32_e32 v217, 0, v23
	v_add_u32_e32 v220, 0, v17
	s_waitcnt vmcnt(0)
	s_waitcnt vmcnt(3)
	ds_write_b128 v219, v[0:3]
	s_waitcnt vmcnt(2)
	ds_write_b128 v220, v[4:7]
	s_waitcnt vmcnt(1)
	ds_write_b128 v217, v[8:11] offset:32768
	s_waitcnt vmcnt(0)
	ds_write_b128 v218, v[12:15] offset:32768
	s_waitcnt lgkmcnt(0)
	s_barrier
	ds_read_b128 v[0:3], v216 offset:32768
	ds_read_b128 v[4:7], v216 offset:40960
	s_waitcnt lgkmcnt(1)
	v_mfma_f32_32x32x16_bf16 v[80:95], v[0:3], v[146:149], 0
	v_or_b32_e32 v0, 32, v194
	v_bitop3_b32 v0, v0, v116, v117 bitop3:0xde
	v_add_u32_e32 v224, 0, v0
	s_waitcnt lgkmcnt(0)
	v_mfma_f32_32x32x16_bf16 v[64:79], v[4:7], v[146:149], 0
	ds_read_b128 v[0:3], v224 offset:32768
	ds_read_b128 v[4:7], v224 offset:40960
	s_waitcnt lgkmcnt(1)
	v_mfma_f32_32x32x16_bf16 v[80:95], v[0:3], v[150:153], v[80:95]
	v_or_b32_e32 v0, 64, v194
	v_bitop3_b32 v0, v0, v116, v117 bitop3:0xde
	v_add_u32_e32 v223, 0, v0
	s_waitcnt lgkmcnt(0)
	v_mfma_f32_32x32x16_bf16 v[64:79], v[4:7], v[150:153], v[64:79]
	ds_read_b128 v[0:3], v223 offset:32768
	ds_read_b128 v[4:7], v223 offset:40960
	s_waitcnt lgkmcnt(1)
	v_mfma_f32_32x32x16_bf16 v[80:95], v[0:3], v[154:157], v[80:95]
	v_or_b32_e32 v0, 0x60, v194
	v_bitop3_b32 v0, v0, v116, v117 bitop3:0xde
	v_add_u32_e32 v221, 0, v0
	s_waitcnt lgkmcnt(0)
	v_mfma_f32_32x32x16_bf16 v[64:79], v[4:7], v[154:157], v[64:79]
	ds_read_b128 v[0:3], v221 offset:32768
	ds_read_b128 v[4:7], v221 offset:40960
	buffer_load_dwordx4 v[96:99], v214, s[92:95], s64 offen
	buffer_load_dwordx4 v[100:103], v215, s[92:95], s64 offen
	buffer_load_dwordx4 v[104:107], v214, s[56:59], s64 offen
	buffer_load_dwordx4 v[108:111], v215, s[56:59], s64 offen
	s_mov_b32 s64, s65
	s_waitcnt lgkmcnt(1)
	v_mfma_f32_32x32x16_bf16 v[80:95], v[0:3], v[158:161], v[80:95]
	v_or_b32_e32 v0, 0x80, v194
	v_bitop3_b32 v0, v0, v116, v117 bitop3:0xde
	v_add_u32_e32 v222, 0, v0
	ds_read_b128 v[0:3], v222 offset:32768
	s_waitcnt lgkmcnt(1)
	v_mfma_f32_32x32x16_bf16 v[64:79], v[4:7], v[158:161], v[64:79]
	ds_read_b128 v[4:7], v222 offset:40960
	s_waitcnt lgkmcnt(1)
	v_mfma_f32_32x32x16_bf16 v[80:95], v[0:3], v[162:165], v[80:95]
	v_or_b32_e32 v0, 0xa0, v194
	v_bitop3_b32 v0, v0, v116, v117 bitop3:0xde
	v_add_u32_e32 v225, 0, v0
	ds_read_b128 v[0:3], v225 offset:32768
	s_waitcnt lgkmcnt(1)
	v_mfma_f32_32x32x16_bf16 v[64:79], v[4:7], v[162:165], v[64:79]
	ds_read_b128 v[4:7], v225 offset:40960
	s_waitcnt lgkmcnt(1)
	v_mfma_f32_32x32x16_bf16 v[80:95], v[0:3], v[166:169], v[80:95]
	v_or_b32_e32 v0, 0xc0, v194
	v_bitop3_b32 v0, v0, v116, v117 bitop3:0xde
	v_add_u32_e32 v226, 0, v0
	ds_read_b128 v[16:19], v226 offset:32768
	ds_read_b128 v[112:115], v226 offset:40960
	v_bitop3_b32 v116, v118, v116, v117 bitop3:0xde
	v_add_u32_e32 v227, 0, v116
	s_waitcnt lgkmcnt(2)
; #define SLOAD(i, k0) do { const unsigned so_ = (unsigned)(k0) * (LDK * 2); \
;     sr_[i].vs0 = BLD8(srV, kvoff, so_); sr_[i].vs1 = BLD8(srV, kvoff + 32u * LDK * 2u, so_); \
;     sr_[i].ks0 = BLD8(srK, kvoff, so_); sr_[i].ks1 = BLD8(srK, kvoff + 32u * LDK * 2u, so_); } while (0)
; #define SWRITE(b, i) do { *(bf16x8*)((char*)V_lds + (b) * SHM_V + vst0) = sr_[i].vs0;          \
;     *(bf16x8*)((char*)V_lds + (b) * SHM_V + vst1) = sr_[i].vs1; int kc = sc * 2;               \
;     *(bf16x8*)((char*)K_lds + (b) * SHM_K + KSWZ(sr, kc)) = sr_[i].ks0;                       \
;     *(bf16x8*)((char*)K_lds + (b) * SHM_K + KSWZ(32 + sr, kc)) = sr_[i].ks1; } while (0)
; #define SWAIT() asm volatile("s_waitcnt vmcnt(0)" ::: "memory")
; template <bool FIRST>
; __device__ __forceinline__ void partialSM(f32x16& p0, f32x16& p1, float& m_reg, f32x16& negm, float& alpha) {
;   float pmax = p0[0]; for (int r = 1; r < 16; ++r) pmax = fmaxf(pmax, p0[r]); for (int r = 0; r < 16; ++r) pmax = fmaxf(pmax, p1[r]);
;   { auto rr = __builtin_amdgcn_permlane32_swap(__float_as_uint(pmax), __float_as_uint(pmax), false, false);
;     pmax = fmaxf(__uint_as_float(rr[0]), __uint_as_float(rr[1])); }
;   if (!FIRST && __builtin_expect(__all(pmax <= THRL), 1)) { alpha = 1.f; }
;   else {
;     const float d = FIRST ? pmax : fmaxf(pmax, 0.f);
;     alpha = FIRST ? 1.f : __builtin_amdgcn_exp2f(-d);
;     m_reg += d;
;     for (int r = 0; r < 16; ++r) p0[r] -= d; for (int r = 0; r < 16; ++r) p1[r] -= d;
;     const float nm = -m_reg; for (int r = 0; r < 16; ++r) negm[r] = nm;
;   }
;   for (int r = 0; r < 16; ++r) p0[r] = __builtin_amdgcn_exp2f(p0[r]);
; }
; __device__ __forceinline__ void attn_dense_body(const bf16* Qb, const bf16* __restrict__ Kh, const bf16* __restrict__ Vh,
;                                                 bf16* Ob, int seq, char* lds, const float* __restrict__ qg, const float* __restrict__ rope, int s0) {
;     ...
;   SLOAD(SE, 0); asm volatile("s_waitcnt vmcnt(0)" ::: "memory"); SWRITE(0, SE); __syncthreads();
;   qkt(pA0, pA1, K_lds, qr, negm, r32, hi); partialSM<true>(pA0, pA1, m_reg, negm, alA);
;   SLOAD(SO, KVBLK);
;   SWAIT(); SWRITE(1, SO); __syncthreads();
	v_mfma_f32_32x32x16_bf16 v[64:79], v[4:7], v[166:169], v[64:79]
	ds_read_b128 v[116:119], v227 offset:32768
	v_mov_b64_e32 v[0:1], s[64:65]
	v_mov_b64_e32 v[14:15], s[78:79]
	v_mov_b64_e32 v[2:3], s[66:67]
	v_mov_b64_e32 v[4:5], s[68:69]
	v_mov_b64_e32 v[6:7], s[70:71]
	v_mov_b64_e32 v[8:9], s[72:73]
	s_waitcnt lgkmcnt(2)
	v_mfma_f32_32x32x16_bf16 v[80:95], v[16:19], v[170:173], v[80:95]
	v_mov_b64_e32 v[10:11], s[74:75]
	v_mov_b64_e32 v[12:13], s[76:77]
	v_mov_b64_e32 v[46:47], v[14:15]
	v_mov_b64_e32 v[30:31], v[14:15]
	v_mov_b64_e32 v[62:63], v[14:15]
	s_mov_b32 s78, 0x800000
	s_mov_b32 s64, 0x8000
	s_waitcnt lgkmcnt(1)
	v_mfma_f32_32x32x16_bf16 v[64:79], v[112:115], v[170:173], v[64:79]
	v_lshlrev_b32_e32 v112, 3, v121
	v_and_b32_e32 v113, 0xc0, v120
	v_and_b32_e32 v120, 32, v123
	v_and_or_b32 v121, v112, 24, v113
	v_and_b32_e32 v123, 0x100, v112
	ds_read_b128 v[112:115], v227 offset:40960
	s_waitcnt vmcnt(0)
	s_waitcnt lgkmcnt(1)
	v_mfma_f32_32x32x16_bf16 v[80:95], v[116:119], v[174:177], v[80:95]
	s_waitcnt vmcnt(3)
	ds_write_b128 v219, v[96:99] offset:16384
	s_waitcnt vmcnt(2)
	ds_write_b128 v220, v[100:103] offset:16384
	s_waitcnt vmcnt(1)
	ds_write_b128 v217, v[104:107] offset:49152
	s_waitcnt vmcnt(0)
	ds_write_b128 v218, v[108:111] offset:49152
	s_waitcnt lgkmcnt(4)
	v_mfma_f32_32x32x16_bf16 v[64:79], v[112:115], v[174:177], v[64:79]
	s_nop 1
	v_max_f32_e32 v112, v81, v81
	v_max_f32_e32 v113, v80, v80
	v_max_f32_e32 v112, v113, v112
	v_max3_f32 v112, v112, v82, v83
	v_max3_f32 v112, v112, v84, v85
	v_max3_f32 v112, v112, v86, v87
	v_max3_f32 v112, v112, v88, v89
	v_max3_f32 v112, v112, v90, v91
	v_max3_f32 v112, v112, v92, v93
	v_max3_f32 v96, v112, v94, v95
	v_max3_f32 v96, v96, v64, v65
	v_max3_f32 v96, v96, v66, v67
	v_max3_f32 v96, v96, v68, v69
	v_max3_f32 v96, v96, v70, v71
	v_max3_f32 v96, v96, v72, v73
	v_max3_f32 v96, v96, v74, v75
	v_max3_f32 v96, v96, v76, v77
	v_max3_f32 v96, v96, v78, v79
	v_mov_b32_e32 v97, v96
	s_nop 1
	v_permlane32_swap_b32_e32 v96, v97
	v_max_f32_e32 v97, v97, v97
	v_max_f32_e32 v96, v96, v96
	v_max_f32_e32 v96, v96, v97
	v_sub_f32_e32 v112, v80, v96
	v_sub_f32_e32 v81, v81, v96
	v_sub_f32_e32 v82, v82, v96
	v_sub_f32_e32 v83, v83, v96
	v_sub_f32_e32 v84, v84, v96
	v_sub_f32_e32 v85, v85, v96
	v_sub_f32_e32 v86, v86, v96
	v_sub_f32_e32 v87, v87, v96
	v_sub_f32_e32 v88, v88, v96
	v_sub_f32_e32 v89, v89, v96
	v_sub_f32_e32 v90, v90, v96
	v_sub_f32_e32 v91, v91, v96
	v_sub_f32_e32 v92, v92, v96
	v_sub_f32_e32 v93, v93, v96
	v_sub_f32_e32 v94, v94, v96
	v_sub_f32_e32 v95, v95, v96
	v_exp_f32_e32 v245, v112
	v_exp_f32_e32 v247, v81
	v_exp_f32_e32 v179, v82
	v_exp_f32_e32 v246, v83
	v_exp_f32_e32 v180, v84
	v_exp_f32_e32 v244, v85
	v_exp_f32_e32 v181, v86
	v_exp_f32_e32 v243, v87
	v_exp_f32_e32 v240, v88
	v_exp_f32_e32 v242, v89
	v_exp_f32_e32 v239, v90
	v_exp_f32_e32 v241, v91
	v_exp_f32_e32 v236, v92
	v_exp_f32_e32 v238, v93
	v_exp_f32_e32 v235, v94
	v_exp_f32_e32 v237, v95
	v_or3_b32 v116, v121, v120, v123
	v_add_f32_e32 v229, 0, v96
	v_add_u32_e32 v213, s26, v116
	s_addk_i32 s26, 0x4000
	v_xor_b32_e32 v80, 0x80000000, v229
	v_mov_b64_e32 v[44:45], v[12:13]
	v_mov_b64_e32 v[42:43], v[10:11]
	v_mov_b64_e32 v[40:41], v[8:9]
	v_mov_b64_e32 v[38:39], v[6:7]
	v_mov_b64_e32 v[36:37], v[4:5]
	v_mov_b64_e32 v[34:35], v[2:3]
	v_mov_b64_e32 v[32:33], v[0:1]
	v_mov_b64_e32 v[28:29], v[12:13]
	v_mov_b64_e32 v[26:27], v[10:11]
	v_mov_b64_e32 v[24:25], v[8:9]
	v_mov_b64_e32 v[22:23], v[6:7]
	v_mov_b64_e32 v[20:21], v[4:5]
	v_mov_b64_e32 v[18:19], v[2:3]
	v_mov_b64_e32 v[16:17], v[0:1]
	v_mov_b64_e32 v[60:61], v[12:13]
	v_mov_b64_e32 v[58:59], v[10:11]
	v_mov_b64_e32 v[56:57], v[8:9]
	v_mov_b64_e32 v[54:55], v[6:7]
	v_mov_b64_e32 v[52:53], v[4:5]
	v_mov_b64_e32 v[50:51], v[2:3]
	v_mov_b64_e32 v[48:49], v[0:1]
	v_add_u32_e32 v212, s26, v116
	v_sub_f32_e32 v111, v79, v96
	v_sub_f32_e32 v110, v78, v96
	v_sub_f32_e32 v109, v77, v96
	v_sub_f32_e32 v108, v76, v96
	v_sub_f32_e32 v107, v75, v96
	v_sub_f32_e32 v106, v74, v96
	v_sub_f32_e32 v105, v73, v96
	v_sub_f32_e32 v104, v72, v96
	v_sub_f32_e32 v103, v71, v96
	v_sub_f32_e32 v102, v70, v96
	v_sub_f32_e32 v101, v69, v96
	v_sub_f32_e32 v100, v68, v96
	v_sub_f32_e32 v99, v67, v96
	v_sub_f32_e32 v98, v66, v96
	v_sub_f32_e32 v97, v65, v96
	v_sub_f32_e32 v96, v64, v96
	v_mov_b32_e32 v81, v80
	v_mov_b32_e32 v82, v80
	v_mov_b32_e32 v83, v80
	v_mov_b32_e32 v84, v80
	v_mov_b32_e32 v85, v80
	v_mov_b32_e32 v86, v80
	v_mov_b32_e32 v87, v80
	v_mov_b32_e32 v88, v80
	v_mov_b32_e32 v89, v80
	v_mov_b32_e32 v90, v80
	v_mov_b32_e32 v91, v80
	v_mov_b32_e32 v92, v80
	v_mov_b32_e32 v93, v80
	v_mov_b32_e32 v94, v80
	v_mov_b32_e32 v95, v80
	s_waitcnt lgkmcnt(0)
	s_barrier

; __device__ __forceinline__ void xcd_barrier(const XcdBarrier& b) {
;     asm volatile("s_waitcnt vmcnt(0)" ::: "memory");
;     __syncthreads();
;     if (threadIdx.x == 0) {
;         unsigned* bar = b.bar;
;         __builtin_amdgcn_s_waitcnt(0);
;         unsigned nloc = b.st[0], nx = b.st[1];
;         if (nloc == 0u) { xcd_barrier_complete(bar, b.x, nloc, nx); b.st[0] = nloc; b.st[1] = nx; }
; __global__ void __launch_bounds__(NTHR, 2) mega_fwd(Args a0) {
;     ...
;         if (p + 1 < ph_hi) { if (p == 0) grid.sync(); else xcd_barrier(xbar); if (PROBE & 16) xcd_barrier(xbar); }
.LBB0_566:
	s_and_b64 vcc, exec, s[34:35]
	s_cbranch_vccz .LBB0_10
	s_add_i32 s0, s82, 1
	s_cmp_ge_i32 s0, s83
	s_cbranch_scc1 .LBB0_10
	v_readlane_b32 s0, v255, 9
	v_readlane_b32 s1, v255, 10
	s_and_b64 vcc, exec, s[0:1]
	s_waitcnt vmcnt(0)
	s_waitcnt vmcnt(1)
	s_barrier
	s_mov_b64 s[0:1], exec
	v_readlane_b32 s16, v253, 4
	v_readlane_b32 s17, v253, 5
	s_and_b64 s[16:17], s[0:1], s[16:17]
	s_mov_b64 exec, s[16:17]
	s_cbranch_execz .LBB0_622
	v_readlane_b32 s16, v254, 56
	s_waitcnt vmcnt(0) expcnt(0) lgkmcnt(0)
	s_nop 0
	v_mov_b32_e32 v0, s16
	ds_read_b32 v2, v0
	v_readlane_b32 s16, v254, 57
	s_waitcnt lgkmcnt(0)
	v_cmp_ne_u32_e32 vcc, 0, v2
	v_mov_b32_e32 v0, s16
	ds_read_b32 v0, v0
	s_cbranch_vccnz .LBB0_586
	s_mov_b32 s19, 1
	s_branch .LBB0_573
